# baseline (speedup 1.0000x reference)
; #define LDA(dst, b, h) for (int m = 0; m < 4; ++m) for (int k = 0; k < 2; ++k) \
;     dst[m][k] = *reinterpret_cast<const bf16x8*>((char*)SA(b, h) + lds_byte(wr * 64 + m * 16 + fr, k * 32 + fq * 8))
; #define LDB(dst, b, h) for (int n = 0; n < 2; ++n) for (int k = 0; k < 2; ++k) \
;     dst[n][k] = *reinterpret_cast<const bf16x8*>((char*)SB(b, h) + lds_byte(wc * 32 + n * 16 + fr, k * 32 + fq * 8))
; #define MMA(ai, bj, At, Bt_) do { __builtin_amdgcn_s_setprio(1); \
;     for (int m = 0; m < 4; ++m) for (int n = 0; n < 2; ++n) for (int k = 0; k < 2; ++k) \
;       acc[ai][bj][m][n] = __builtin_amdgcn_mfma_f32_16x16x32_bf16(At[m][k], Bt_[n][k], acc[ai][bj][m][n], 0, 0, 0); \
;     __builtin_amdgcn_s_setprio(0); } while (0)
; #define WAIT_V(n) asm volatile("s_waitcnt vmcnt(" #n ")" ::: "memory")
; #define WAIT_L(n) asm volatile("s_waitcnt lgkmcnt(" #n ")" ::: "memory")
; #define BAR __builtin_amdgcn_s_barrier()
; #define SCHED __builtin_amdgcn_sched_barrier(0)
; __device__ __forceinline__ void gemm_tile(const bf16_t* __restrict__ A, const bf16_t* __restrict__ Bt, int K, int brow, int bcol,
;                                           int mode, const Params& p, char* wsb, const float* xg, float* outg, int S, char* shmc) {
;     ...
;   for (int t = 0; t < nt - 2; t += 2) {
;     LDB(B0, 0, 0); SCHED; LDA(At, 0, 0); STAGE(SA(1, 1), A, 0, brow + HALF, t + 1);
;     WAIT_L(8); BAR; WAIT_L(0); MMA(0, 0, At, B0); BAR; SCHED;
;     LDB(B1, 0, 1); STAGE(SB(0, 0), Bt, 0, bcol, t + 2);
;     BAR; WAIT_L(0); MMA(0, 1, At, B1); BAR;
;     LDA(At, 0, 1); STAGE(SA(0, 0), A, 0, brow, t + 2);
;     BAR; WAIT_L(0); MMA(1, 0, At, B0); BAR; SCHED;
;     STAGE(SB(0, 1), Bt, 0, bcol + HALF, t + 2);
;     WAIT_V(6); BAR; MMA(1, 1, At, B1); BAR;
.LBB0_169:
	ds_read_b128 v[134:137], v133
	ds_read_b128 v[138:141], v133 offset:1024
	ds_read_b128 v[142:145], v133 offset:2048
	ds_read_b128 v[146:149], v133 offset:3072
	s_add_u32 vcc_lo, s42, s14
	s_addc_u32 vcc_hi, s43, s15
	s_add_u32 s68, vcc_lo, 0x80
	s_addc_u32 s69, vcc_hi, 0
	s_add_i32 s98, s22, 0xc000
	s_mov_b32 m0, s98
	s_add_i32 s99, s22, 0xe000
	ds_read_b128 v[150:153], v171
	ds_read_b128 v[154:157], v171 offset:1024
	ds_read_b128 v[188:191], v170
	ds_read_b128 v[192:195], v170 offset:1024
	ds_read_b128 v[196:199], v169
	ds_read_b128 v[200:203], v169 offset:1024
	ds_read_b128 v[204:207], v167
	ds_read_b128 v[208:211], v167 offset:1024
	s_nop 0
	global_load_lds_dwordx4 v128, s[68:69]
	s_mov_b32 m0, s99
	s_nop 0
	global_load_lds_dwordx4 v129, s[68:69]
	s_waitcnt lgkmcnt(8)
	s_barrier
	s_waitcnt lgkmcnt(0)
	s_setprio 1
	s_waitcnt lgkmcnt(0)
	v_mfma_f32_16x16x32_bf16 v[124:127], v[150:153], v[134:137], v[124:127]
	v_mfma_f32_16x16x32_bf16 v[120:123], v[150:153], v[142:145], v[120:123]
	v_mfma_f32_16x16x32_bf16 v[116:119], v[188:191], v[134:137], v[116:119]
	v_mfma_f32_16x16x32_bf16 v[112:115], v[188:191], v[142:145], v[112:115]
	v_mfma_f32_16x16x32_bf16 v[108:111], v[196:199], v[134:137], v[108:111]
	v_mfma_f32_16x16x32_bf16 v[104:107], v[196:199], v[142:145], v[104:107]
	v_mfma_f32_16x16x32_bf16 v[100:103], v[204:207], v[134:137], v[100:103]
	v_mfma_f32_16x16x32_bf16 v[96:99], v[204:207], v[142:145], v[96:99]
	v_mfma_f32_16x16x32_bf16 v[124:127], v[154:157], v[138:141], v[124:127]
	v_mfma_f32_16x16x32_bf16 v[120:123], v[154:157], v[146:149], v[120:123]
	v_mfma_f32_16x16x32_bf16 v[116:119], v[192:195], v[138:141], v[116:119]
	v_mfma_f32_16x16x32_bf16 v[112:115], v[192:195], v[146:149], v[112:115]
	s_add_i32 s44, s44, 2
	s_add_u32 s51, s4, s14
	s_addc_u32 s72, s5, s15
	s_add_u32 s68, s51, 0x100
	s_addc_u32 s69, s72, 0
	v_mfma_f32_16x16x32_bf16 v[108:111], v[200:203], v[138:141], v[108:111]
	v_mfma_f32_16x16x32_bf16 v[104:107], v[200:203], v[146:149], v[104:107]
	v_mfma_f32_16x16x32_bf16 v[100:103], v[208:211], v[138:141], v[100:103]
	v_mfma_f32_16x16x32_bf16 v[96:99], v[208:211], v[146:149], v[96:99]
	s_setprio 0
	s_barrier
	s_mov_b32 m0, s23
	ds_read_b128 v[212:215], v132
	ds_read_b128 v[216:219], v132 offset:1024
	ds_read_b128 v[220:223], v132 offset:2048
	ds_read_b128 v[224:227], v132 offset:3072
	s_nop 0
	global_load_lds_dwordx4 v128, s[68:69]
	s_mov_b32 m0, s24
	s_nop 0
	global_load_lds_dwordx4 v129, s[68:69]
	s_barrier
	s_waitcnt lgkmcnt(0)
	s_setprio 1
	s_waitcnt lgkmcnt(0)
	v_mfma_f32_16x16x32_bf16 v[92:95], v[150:153], v[212:215], v[92:95]
	v_mfma_f32_16x16x32_bf16 v[88:91], v[150:153], v[220:223], v[88:91]
	v_mfma_f32_16x16x32_bf16 v[84:87], v[188:191], v[212:215], v[84:87]
	v_mfma_f32_16x16x32_bf16 v[80:83], v[188:191], v[220:223], v[80:83]
	v_mfma_f32_16x16x32_bf16 v[76:79], v[196:199], v[212:215], v[76:79]
	v_mfma_f32_16x16x32_bf16 v[72:75], v[196:199], v[220:223], v[72:75]
	v_mfma_f32_16x16x32_bf16 v[68:71], v[204:207], v[212:215], v[68:71]
	v_mfma_f32_16x16x32_bf16 v[64:67], v[204:207], v[220:223], v[64:67]
	v_mfma_f32_16x16x32_bf16 v[92:95], v[154:157], v[216:219], v[92:95]
	v_mfma_f32_16x16x32_bf16 v[88:91], v[154:157], v[224:227], v[88:91]
	v_mfma_f32_16x16x32_bf16 v[84:87], v[192:195], v[216:219], v[84:87]
	v_mfma_f32_16x16x32_bf16 v[80:83], v[192:195], v[224:227], v[80:83]
	v_mfma_f32_16x16x32_bf16 v[76:79], v[200:203], v[216:219], v[76:79]
	v_mfma_f32_16x16x32_bf16 v[72:75], v[200:203], v[224:227], v[72:75]
	v_mfma_f32_16x16x32_bf16 v[68:71], v[208:211], v[216:219], v[68:71]
	v_mfma_f32_16x16x32_bf16 v[64:67], v[208:211], v[224:227], v[64:67]
	s_setprio 0
	s_add_u32 s73, s20, s14
	s_addc_u32 s78, s21, s15
	s_add_u32 s68, s73, 0x100
	s_addc_u32 s69, s78, 0
	s_mov_b32 m0, s22
	s_barrier
	ds_read_b128 v[150:153], v171 offset:16384
	ds_read_b128 v[154:157], v171 offset:17408
	ds_read_b128 v[188:191], v170 offset:16384
	ds_read_b128 v[192:195], v170 offset:17408
	ds_read_b128 v[196:199], v169 offset:16384
	ds_read_b128 v[200:203], v169 offset:17408
	ds_read_b128 v[204:207], v167 offset:16384
	ds_read_b128 v[208:211], v167 offset:17408
	s_nop 0
	global_load_lds_dwordx4 v128, s[68:69]
	s_mov_b32 m0, s25
	s_nop 0
	global_load_lds_dwordx4 v129, s[68:69]
	s_barrier
	s_waitcnt lgkmcnt(0)
	s_setprio 1
	s_waitcnt lgkmcnt(0)
	v_mfma_f32_16x16x32_bf16 v[60:63], v[150:153], v[134:137], v[60:63]
	v_mfma_f32_16x16x32_bf16 v[56:59], v[150:153], v[142:145], v[56:59]
	v_mfma_f32_16x16x32_bf16 v[52:55], v[188:191], v[134:137], v[52:55]
	v_mfma_f32_16x16x32_bf16 v[48:51], v[188:191], v[142:145], v[48:51]
	v_mfma_f32_16x16x32_bf16 v[44:47], v[196:199], v[134:137], v[44:47]
	v_mfma_f32_16x16x32_bf16 v[40:43], v[196:199], v[142:145], v[40:43]
	v_mfma_f32_16x16x32_bf16 v[36:39], v[204:207], v[134:137], v[36:39]
	v_mfma_f32_16x16x32_bf16 v[32:35], v[204:207], v[142:145], v[32:35]
	v_mfma_f32_16x16x32_bf16 v[60:63], v[154:157], v[138:141], v[60:63]
	v_mfma_f32_16x16x32_bf16 v[56:59], v[154:157], v[146:149], v[56:59]
	v_mfma_f32_16x16x32_bf16 v[52:55], v[192:195], v[138:141], v[52:55]
	v_mfma_f32_16x16x32_bf16 v[48:51], v[192:195], v[146:149], v[48:51]
	s_add_u32 s79, s16, s14
	s_addc_u32 s80, s17, s15
	s_add_u32 s68, s79, 0x100
	s_addc_u32 s69, s80, 0
	v_mfma_f32_16x16x32_bf16 v[44:47], v[200:203], v[138:141], v[44:47]
	v_mfma_f32_16x16x32_bf16 v[40:43], v[200:203], v[146:149], v[40:43]
	v_mfma_f32_16x16x32_bf16 v[36:39], v[208:211], v[138:141], v[36:39]
	v_mfma_f32_16x16x32_bf16 v[32:35], v[208:211], v[146:149], v[32:35]
	s_setprio 0
	s_barrier
	s_mov_b32 m0, s26
	s_nop 0
	global_load_lds_dwordx4 v128, s[68:69]
	s_mov_b32 m0, s27
	s_nop 0
	global_load_lds_dwordx4 v129, s[68:69]
	s_waitcnt vmcnt(6)
	s_barrier
; #define LDA(dst, b, h) for (int m = 0; m < 4; ++m) for (int k = 0; k < 2; ++k) \
;     dst[m][k] = *reinterpret_cast<const bf16x8*>((char*)SA(b, h) + lds_byte(wr * 64 + m * 16 + fr, k * 32 + fq * 8))
; #define LDB(dst, b, h) for (int n = 0; n < 2; ++n) for (int k = 0; k < 2; ++k) \
;     dst[n][k] = *reinterpret_cast<const bf16x8*>((char*)SB(b, h) + lds_byte(wc * 32 + n * 16 + fr, k * 32 + fq * 8))
; #define MMA(ai, bj, At, Bt_) do { __builtin_amdgcn_s_setprio(1); \
;     for (int m = 0; m < 4; ++m) for (int n = 0; n < 2; ++n) for (int k = 0; k < 2; ++k) \
;       acc[ai][bj][m][n] = __builtin_amdgcn_mfma_f32_16x16x32_bf16(At[m][k], Bt_[n][k], acc[ai][bj][m][n], 0, 0, 0); \
;     __builtin_amdgcn_s_setprio(0); } while (0)
; #define WAIT_V(n) asm volatile("s_waitcnt vmcnt(" #n ")" ::: "memory")
; #define WAIT_L(n) asm volatile("s_waitcnt lgkmcnt(" #n ")" ::: "memory")
; #define BAR __builtin_amdgcn_s_barrier()
; #define SCHED __builtin_amdgcn_sched_barrier(0)
; __device__ __forceinline__ void gemm_tile(const bf16_t* __restrict__ A, const bf16_t* __restrict__ Bt, int K, int brow, int bcol,
;                                           int mode, const Params& p, char* wsb, const float* xg, float* outg, int S, char* shmc) {
;     ...
;     WAIT_V(6); BAR; MMA(1, 1, At, B1); BAR;
;     LDB(B0, 1, 0); SCHED; LDA(At, 1, 0); STAGE(SA(0, 1), A, 0, brow + HALF, t + 2);
;     WAIT_L(8); BAR; WAIT_L(0); MMA(0, 0, At, B0); BAR; SCHED;
;     LDB(B1, 1, 1); STAGE(SB(1, 0), Bt, 0, bcol, t + 3);
;     BAR; WAIT_L(0); MMA(0, 1, At, B1); BAR;
;     LDA(At, 1, 1); STAGE(SA(1, 0), A, 0, brow, t + 3);
;     BAR; WAIT_L(0); MMA(1, 0, At, B0); BAR; SCHED;
	s_setprio 1
	v_mfma_f32_16x16x32_bf16 v[28:31], v[150:153], v[212:215], v[28:31]
	v_mfma_f32_16x16x32_bf16 v[24:27], v[150:153], v[220:223], v[24:27]
	v_mfma_f32_16x16x32_bf16 v[20:23], v[188:191], v[212:215], v[20:23]
	v_mfma_f32_16x16x32_bf16 v[16:19], v[188:191], v[220:223], v[16:19]
	v_mfma_f32_16x16x32_bf16 v[12:15], v[196:199], v[212:215], v[12:15]
	v_mfma_f32_16x16x32_bf16 v[8:11], v[196:199], v[220:223], v[8:11]
	v_mfma_f32_16x16x32_bf16 v[4:7], v[204:207], v[212:215], v[4:7]
	v_mfma_f32_16x16x32_bf16 v[0:3], v[204:207], v[220:223], v[0:3]
	v_mfma_f32_16x16x32_bf16 v[28:31], v[154:157], v[216:219], v[28:31]
	v_mfma_f32_16x16x32_bf16 v[24:27], v[154:157], v[224:227], v[24:27]
	v_mfma_f32_16x16x32_bf16 v[20:23], v[192:195], v[216:219], v[20:23]
	v_mfma_f32_16x16x32_bf16 v[16:19], v[192:195], v[224:227], v[16:19]
	v_mfma_f32_16x16x32_bf16 v[12:15], v[200:203], v[216:219], v[12:15]
	v_mfma_f32_16x16x32_bf16 v[8:11], v[200:203], v[224:227], v[8:11]
	v_mfma_f32_16x16x32_bf16 v[4:7], v[208:211], v[216:219], v[4:7]
	v_mfma_f32_16x16x32_bf16 v[0:3], v[208:211], v[224:227], v[0:3]
	s_setprio 0
	s_barrier
	ds_read_b128 v[134:137], v131
	ds_read_b128 v[138:141], v131 offset:1024
	ds_read_b128 v[142:145], v131 offset:2048
	ds_read_b128 v[146:149], v131 offset:3072
	s_add_u32 s68, vcc_lo, 0x100
	s_addc_u32 s69, vcc_hi, 0
	s_mov_b32 m0, s40
	ds_read_b128 v[150:153], v171 offset:32768
	ds_read_b128 v[154:157], v171 offset:33792
	ds_read_b128 v[188:191], v170 offset:32768
	ds_read_b128 v[192:195], v170 offset:33792
	ds_read_b128 v[196:199], v169 offset:32768
	ds_read_b128 v[200:203], v169 offset:33792
	ds_read_b128 v[204:207], v167 offset:32768
	ds_read_b128 v[208:211], v167 offset:33792
	s_nop 0
	global_load_lds_dwordx4 v128, s[68:69]
	s_mov_b32 m0, s41
	s_nop 0
	global_load_lds_dwordx4 v129, s[68:69]
	s_waitcnt lgkmcnt(8)
	s_barrier
	s_waitcnt lgkmcnt(0)
	s_setprio 1
	s_waitcnt lgkmcnt(0)
	v_mfma_f32_16x16x32_bf16 v[124:127], v[150:153], v[134:137], v[124:127]
	v_mfma_f32_16x16x32_bf16 v[120:123], v[150:153], v[142:145], v[120:123]
	v_mfma_f32_16x16x32_bf16 v[116:119], v[188:191], v[134:137], v[116:119]
	v_mfma_f32_16x16x32_bf16 v[112:115], v[188:191], v[142:145], v[112:115]
	v_mfma_f32_16x16x32_bf16 v[108:111], v[196:199], v[134:137], v[108:111]
	v_mfma_f32_16x16x32_bf16 v[104:107], v[196:199], v[142:145], v[104:107]
	v_mfma_f32_16x16x32_bf16 v[100:103], v[204:207], v[134:137], v[100:103]
	v_mfma_f32_16x16x32_bf16 v[96:99], v[204:207], v[142:145], v[96:99]
	v_mfma_f32_16x16x32_bf16 v[124:127], v[154:157], v[138:141], v[124:127]
	v_mfma_f32_16x16x32_bf16 v[120:123], v[154:157], v[146:149], v[120:123]
	v_mfma_f32_16x16x32_bf16 v[116:119], v[192:195], v[138:141], v[116:119]
	v_mfma_f32_16x16x32_bf16 v[112:115], v[192:195], v[146:149], v[112:115]
	s_add_u32 s68, s51, 0x180
	s_addc_u32 s69, s72, 0
	v_mfma_f32_16x16x32_bf16 v[108:111], v[200:203], v[138:141], v[108:111]
	v_mfma_f32_16x16x32_bf16 v[104:107], v[200:203], v[146:149], v[104:107]
	v_mfma_f32_16x16x32_bf16 v[100:103], v[208:211], v[138:141], v[100:103]
	v_mfma_f32_16x16x32_bf16 v[96:99], v[208:211], v[146:149], v[96:99]
	s_setprio 0
	s_barrier
	s_add_i32 m0, s22, 0x18000
	ds_read_b128 v[212:215], v130
	ds_read_b128 v[216:219], v130 offset:1024
	ds_read_b128 v[220:223], v130 offset:2048
	ds_read_b128 v[224:227], v130 offset:3072
	s_nop 0
	global_load_lds_dwordx4 v128, s[68:69]
	s_add_i32 m0, s22, 0x1a000
	s_nop 0
	global_load_lds_dwordx4 v129, s[68:69]
	s_barrier
	s_waitcnt lgkmcnt(0)
	s_setprio 1
	s_waitcnt lgkmcnt(0)
	v_mfma_f32_16x16x32_bf16 v[92:95], v[150:153], v[212:215], v[92:95]
	v_mfma_f32_16x16x32_bf16 v[88:91], v[150:153], v[220:223], v[88:91]
	v_mfma_f32_16x16x32_bf16 v[84:87], v[188:191], v[212:215], v[84:87]
	v_mfma_f32_16x16x32_bf16 v[80:83], v[188:191], v[220:223], v[80:83]
	v_mfma_f32_16x16x32_bf16 v[76:79], v[196:199], v[212:215], v[76:79]
	v_mfma_f32_16x16x32_bf16 v[72:75], v[196:199], v[220:223], v[72:75]
	v_mfma_f32_16x16x32_bf16 v[68:71], v[204:207], v[212:215], v[68:71]
	v_mfma_f32_16x16x32_bf16 v[64:67], v[204:207], v[220:223], v[64:67]
	v_mfma_f32_16x16x32_bf16 v[92:95], v[154:157], v[216:219], v[92:95]
	v_mfma_f32_16x16x32_bf16 v[88:91], v[154:157], v[224:227], v[88:91]
	v_mfma_f32_16x16x32_bf16 v[84:87], v[192:195], v[216:219], v[84:87]
	v_mfma_f32_16x16x32_bf16 v[80:83], v[192:195], v[224:227], v[80:83]
	v_mfma_f32_16x16x32_bf16 v[76:79], v[200:203], v[216:219], v[76:79]
	v_mfma_f32_16x16x32_bf16 v[72:75], v[200:203], v[224:227], v[72:75]
	v_mfma_f32_16x16x32_bf16 v[68:71], v[208:211], v[216:219], v[68:71]
	v_mfma_f32_16x16x32_bf16 v[64:67], v[208:211], v[224:227], v[64:67]
	s_setprio 0
	s_add_u32 s68, s73, 0x180
	s_addc_u32 s69, s78, 0
	s_mov_b32 m0, s18
	s_barrier
	ds_read_b128 v[150:153], v171 offset:49152
	ds_read_b128 v[154:157], v171 offset:50176
	ds_read_b128 v[188:191], v170 offset:49152
	ds_read_b128 v[192:195], v170 offset:50176
	ds_read_b128 v[196:199], v169 offset:49152
	ds_read_b128 v[200:203], v169 offset:50176
	ds_read_b128 v[204:207], v167 offset:49152
	ds_read_b128 v[208:211], v167 offset:50176
	s_nop 0
	global_load_lds_dwordx4 v128, s[68:69]
	s_mov_b32 m0, s19
	s_nop 0
	global_load_lds_dwordx4 v129, s[68:69]
	s_barrier
; #define LDA(dst, b, h) for (int m = 0; m < 4; ++m) for (int k = 0; k < 2; ++k) \
;     dst[m][k] = *reinterpret_cast<const bf16x8*>((char*)SA(b, h) + lds_byte(wr * 64 + m * 16 + fr, k * 32 + fq * 8))
; #define LDB(dst, b, h) for (int n = 0; n < 2; ++n) for (int k = 0; k < 2; ++k) \
;     dst[n][k] = *reinterpret_cast<const bf16x8*>((char*)SB(b, h) + lds_byte(wc * 32 + n * 16 + fr, k * 32 + fq * 8))
; #define MMA(ai, bj, At, Bt_) do { __builtin_amdgcn_s_setprio(1); \
;     for (int m = 0; m < 4; ++m) for (int n = 0; n < 2; ++n) for (int k = 0; k < 2; ++k) \
;       acc[ai][bj][m][n] = __builtin_amdgcn_mfma_f32_16x16x32_bf16(At[m][k], Bt_[n][k], acc[ai][bj][m][n], 0, 0, 0); \
;     __builtin_amdgcn_s_setprio(0); } while (0)
; #define WAIT_V(n) asm volatile("s_waitcnt vmcnt(" #n ")" ::: "memory")
; #define WAIT_L(n) asm volatile("s_waitcnt lgkmcnt(" #n ")" ::: "memory")
; #define BAR __builtin_amdgcn_s_barrier()
; #define SCHED __builtin_amdgcn_sched_barrier(0)
; __device__ __forceinline__ void gemm_tile(const bf16_t* __restrict__ A, const bf16_t* __restrict__ Bt, int K, int brow, int bcol,
;                                           int mode, const Params& p, char* wsb, const float* xg, float* outg, int S, char* shmc) {
;     ...
;     BAR; WAIT_L(0); MMA(1, 0, At, B0); BAR; SCHED;
;     STAGE(SB(1, 1), Bt, 0, bcol + HALF, t + 3);
;     WAIT_V(6); BAR; MMA(1, 1, At, B1); BAR;
;   }
;   { LDB(B0, 0, 0); LDA(At, 0, 0); STAGE(SA(1, 1), A, 0, brow + HALF, nt - 1);
;     BAR; WAIT_L(0); MMA(0, 0, At, B0); BAR;
;     LDB(B1, 0, 1); BAR; WAIT_L(0); MMA(0, 1, At, B1); BAR;
;     LDA(At, 0, 1); WAIT_V(4); BAR; WAIT_L(0); MMA(1, 0, At, B0); MMA(1, 1, At, B1); BAR; }
	s_waitcnt lgkmcnt(0)
	s_setprio 1
	s_waitcnt lgkmcnt(0)
	v_mfma_f32_16x16x32_bf16 v[60:63], v[150:153], v[134:137], v[60:63]
	v_mfma_f32_16x16x32_bf16 v[56:59], v[150:153], v[142:145], v[56:59]
	v_mfma_f32_16x16x32_bf16 v[52:55], v[188:191], v[134:137], v[52:55]
	v_mfma_f32_16x16x32_bf16 v[48:51], v[188:191], v[142:145], v[48:51]
	v_mfma_f32_16x16x32_bf16 v[44:47], v[196:199], v[134:137], v[44:47]
	v_mfma_f32_16x16x32_bf16 v[40:43], v[196:199], v[142:145], v[40:43]
	v_mfma_f32_16x16x32_bf16 v[36:39], v[204:207], v[134:137], v[36:39]
	v_mfma_f32_16x16x32_bf16 v[32:35], v[204:207], v[142:145], v[32:35]
	v_mfma_f32_16x16x32_bf16 v[60:63], v[154:157], v[138:141], v[60:63]
	v_mfma_f32_16x16x32_bf16 v[56:59], v[154:157], v[146:149], v[56:59]
	v_mfma_f32_16x16x32_bf16 v[52:55], v[192:195], v[138:141], v[52:55]
	v_mfma_f32_16x16x32_bf16 v[48:51], v[192:195], v[146:149], v[48:51]
	s_add_u32 s68, s79, 0x180
	s_addc_u32 s69, s80, 0
	v_mfma_f32_16x16x32_bf16 v[44:47], v[200:203], v[138:141], v[44:47]
	v_mfma_f32_16x16x32_bf16 v[40:43], v[200:203], v[146:149], v[40:43]
	v_mfma_f32_16x16x32_bf16 v[36:39], v[208:211], v[138:141], v[36:39]
	v_mfma_f32_16x16x32_bf16 v[32:35], v[208:211], v[146:149], v[32:35]
	s_setprio 0
	s_barrier
	s_add_i32 m0, s22, 0x1c000
	s_nop 0
	global_load_lds_dwordx4 v128, s[68:69]
	s_add_i32 m0, s22, 0x1e000
	s_nop 0
	global_load_lds_dwordx4 v129, s[68:69]
	s_waitcnt vmcnt(6)
	s_barrier
	s_setprio 1
	v_mfma_f32_16x16x32_bf16 v[28:31], v[150:153], v[212:215], v[28:31]
	v_mfma_f32_16x16x32_bf16 v[24:27], v[150:153], v[220:223], v[24:27]
	v_mfma_f32_16x16x32_bf16 v[20:23], v[188:191], v[212:215], v[20:23]
	v_mfma_f32_16x16x32_bf16 v[16:19], v[188:191], v[220:223], v[16:19]
	v_mfma_f32_16x16x32_bf16 v[12:15], v[196:199], v[212:215], v[12:15]
	v_mfma_f32_16x16x32_bf16 v[8:11], v[196:199], v[220:223], v[8:11]
	v_mfma_f32_16x16x32_bf16 v[4:7], v[204:207], v[212:215], v[4:7]
	v_mfma_f32_16x16x32_bf16 v[0:3], v[204:207], v[220:223], v[0:3]
	v_mfma_f32_16x16x32_bf16 v[28:31], v[154:157], v[216:219], v[28:31]
	v_mfma_f32_16x16x32_bf16 v[24:27], v[154:157], v[224:227], v[24:27]
	v_mfma_f32_16x16x32_bf16 v[20:23], v[192:195], v[216:219], v[20:23]
	v_mfma_f32_16x16x32_bf16 v[16:19], v[192:195], v[224:227], v[16:19]
	v_mfma_f32_16x16x32_bf16 v[12:15], v[200:203], v[216:219], v[12:15]
	v_mfma_f32_16x16x32_bf16 v[8:11], v[200:203], v[224:227], v[8:11]
	v_mfma_f32_16x16x32_bf16 v[4:7], v[208:211], v[216:219], v[4:7]
	v_mfma_f32_16x16x32_bf16 v[0:3], v[208:211], v[224:227], v[0:3]
	s_setprio 0
	s_add_u32 s14, s14, 0x100
	s_addc_u32 s15, s15, 0
	s_cmp_lt_u32 s44, s70
	s_barrier
	s_cbranch_scc1 .LBB0_169
	s_add_u32 s4, s12, s64
	s_addc_u32 s5, s13, s65
	s_mov_b32 m0, s98
	ds_read_b128 v[134:137], v133
	ds_read_b128 v[138:141], v133 offset:1024
	ds_read_b128 v[142:145], v133 offset:2048
	ds_read_b128 v[146:149], v133 offset:3072
	ds_read_b128 v[150:153], v171
	ds_read_b128 v[154:157], v171 offset:1024
	ds_read_b128 v[188:191], v170
	ds_read_b128 v[192:195], v170 offset:1024
	ds_read_b128 v[196:199], v169
	ds_read_b128 v[200:203], v169 offset:1024
	ds_read_b128 v[204:207], v167
	ds_read_b128 v[208:211], v167 offset:1024
	s_nop 0
	global_load_lds_dwordx4 v128, s[4:5]
	s_mov_b32 m0, s99
	s_nop 0
	global_load_lds_dwordx4 v129, s[4:5]
	s_barrier
	s_waitcnt lgkmcnt(0)
	s_setprio 1
	s_waitcnt lgkmcnt(0)
	v_mfma_f32_16x16x32_bf16 v[124:127], v[150:153], v[134:137], v[124:127]
	v_mfma_f32_16x16x32_bf16 v[120:123], v[150:153], v[142:145], v[120:123]
	v_mfma_f32_16x16x32_bf16 v[116:119], v[188:191], v[134:137], v[116:119]
	v_mfma_f32_16x16x32_bf16 v[112:115], v[188:191], v[142:145], v[112:115]
	v_mfma_f32_16x16x32_bf16 v[108:111], v[196:199], v[134:137], v[108:111]
	v_mfma_f32_16x16x32_bf16 v[104:107], v[196:199], v[142:145], v[104:107]
	v_mfma_f32_16x16x32_bf16 v[100:103], v[204:207], v[134:137], v[100:103]
	v_mfma_f32_16x16x32_bf16 v[96:99], v[204:207], v[142:145], v[96:99]
	v_mfma_f32_16x16x32_bf16 v[124:127], v[154:157], v[138:141], v[124:127]
	v_mfma_f32_16x16x32_bf16 v[120:123], v[154:157], v[146:149], v[120:123]
	v_mfma_f32_16x16x32_bf16 v[116:119], v[192:195], v[138:141], v[116:119]
	v_mfma_f32_16x16x32_bf16 v[112:115], v[192:195], v[146:149], v[112:115]
	v_mfma_f32_16x16x32_bf16 v[108:111], v[200:203], v[138:141], v[108:111]
	v_mfma_f32_16x16x32_bf16 v[104:107], v[200:203], v[146:149], v[104:107]
	v_mfma_f32_16x16x32_bf16 v[100:103], v[208:211], v[138:141], v[100:103]
	v_mfma_f32_16x16x32_bf16 v[96:99], v[208:211], v[146:149], v[96:99]
	s_setprio 0
	s_barrier
	ds_read_b128 v[212:215], v132
	ds_read_b128 v[216:219], v132 offset:1024
	ds_read_b128 v[220:223], v132 offset:2048
	ds_read_b128 v[224:227], v132 offset:3072
	s_barrier
	s_waitcnt lgkmcnt(0)
	s_setprio 1
	s_waitcnt lgkmcnt(0)
	v_mfma_f32_16x16x32_bf16 v[92:95], v[150:153], v[212:215], v[92:95]
	v_mfma_f32_16x16x32_bf16 v[88:91], v[150:153], v[220:223], v[88:91]
	v_mfma_f32_16x16x32_bf16 v[84:87], v[188:191], v[212:215], v[84:87]
	v_mfma_f32_16x16x32_bf16 v[80:83], v[188:191], v[220:223], v[80:83]
	v_mfma_f32_16x16x32_bf16 v[76:79], v[196:199], v[212:215], v[76:79]
	v_mfma_f32_16x16x32_bf16 v[72:75], v[196:199], v[220:223], v[72:75]
	v_mfma_f32_16x16x32_bf16 v[68:71], v[204:207], v[212:215], v[68:71]
	v_mfma_f32_16x16x32_bf16 v[64:67], v[204:207], v[220:223], v[64:67]
	v_mfma_f32_16x16x32_bf16 v[92:95], v[154:157], v[216:219], v[92:95]
	v_mfma_f32_16x16x32_bf16 v[88:91], v[154:157], v[224:227], v[88:91]
	v_mfma_f32_16x16x32_bf16 v[84:87], v[192:195], v[216:219], v[84:87]
	v_mfma_f32_16x16x32_bf16 v[80:83], v[192:195], v[224:227], v[80:83]
	v_mfma_f32_16x16x32_bf16 v[76:79], v[200:203], v[216:219], v[76:79]
	v_mfma_f32_16x16x32_bf16 v[72:75], v[200:203], v[224:227], v[72:75]
	v_mfma_f32_16x16x32_bf16 v[68:71], v[208:211], v[216:219], v[68:71]
	v_mfma_f32_16x16x32_bf16 v[64:67], v[208:211], v[224:227], v[64:67]
	s_setprio 0
	s_barrier
; #define LDA(dst, b, h) for (int m = 0; m < 4; ++m) for (int k = 0; k < 2; ++k) \
;     dst[m][k] = *reinterpret_cast<const bf16x8*>((char*)SA(b, h) + lds_byte(wr * 64 + m * 16 + fr, k * 32 + fq * 8))
; #define LDB(dst, b, h) for (int n = 0; n < 2; ++n) for (int k = 0; k < 2; ++k) \
;     dst[n][k] = *reinterpret_cast<const bf16x8*>((char*)SB(b, h) + lds_byte(wc * 32 + n * 16 + fr, k * 32 + fq * 8))
; #define MMA(ai, bj, At, Bt_) do { __builtin_amdgcn_s_setprio(1); \
;     for (int m = 0; m < 4; ++m) for (int n = 0; n < 2; ++n) for (int k = 0; k < 2; ++k) \
;       acc[ai][bj][m][n] = __builtin_amdgcn_mfma_f32_16x16x32_bf16(At[m][k], Bt_[n][k], acc[ai][bj][m][n], 0, 0, 0); \
;     __builtin_amdgcn_s_setprio(0); } while (0)
; #define WAIT_V(n) asm volatile("s_waitcnt vmcnt(" #n ")" ::: "memory")
; #define WAIT_L(n) asm volatile("s_waitcnt lgkmcnt(" #n ")" ::: "memory")
; #define BAR __builtin_amdgcn_s_barrier()
; __device__ __forceinline__ void gemm_tile(const bf16_t* __restrict__ A, const bf16_t* __restrict__ Bt, int K, int brow, int bcol,
;                                           int mode, const Params& p, char* wsb, const float* xg, float* outg, int S, char* shmc) {
;     ...
;     LDA(At, 0, 1); WAIT_V(4); BAR; WAIT_L(0); MMA(1, 0, At, B0); MMA(1, 1, At, B1); BAR; }
;   { LDB(B0, 1, 0); LDA(At, 1, 0); WAIT_V(2); BAR; WAIT_L(0); MMA(0, 0, At, B0); BAR;
;     LDB(B1, 1, 1); WAIT_V(0); BAR; WAIT_L(0); MMA(0, 1, At, B1); BAR;
;     LDA(At, 1, 1); BAR; WAIT_L(0); MMA(1, 0, At, B0); MMA(1, 1, At, B1); BAR; }
	ds_read_b128 v[150:153], v171 offset:16384
	ds_read_b128 v[154:157], v171 offset:17408
	ds_read_b128 v[188:191], v170 offset:16384
	ds_read_b128 v[192:195], v170 offset:17408
	ds_read_b128 v[196:199], v169 offset:16384
	ds_read_b128 v[200:203], v169 offset:17408
	ds_read_b128 v[204:207], v167 offset:16384
	ds_read_b128 v[208:211], v167 offset:17408
	s_waitcnt vmcnt(4)
	s_barrier
	s_waitcnt lgkmcnt(0)
	s_setprio 1
	s_waitcnt lgkmcnt(0)
	v_mfma_f32_16x16x32_bf16 v[60:63], v[150:153], v[134:137], v[60:63]
	v_mfma_f32_16x16x32_bf16 v[56:59], v[150:153], v[142:145], v[56:59]
	v_mfma_f32_16x16x32_bf16 v[52:55], v[188:191], v[134:137], v[52:55]
	v_mfma_f32_16x16x32_bf16 v[48:51], v[188:191], v[142:145], v[48:51]
	v_mfma_f32_16x16x32_bf16 v[44:47], v[196:199], v[134:137], v[44:47]
	v_mfma_f32_16x16x32_bf16 v[40:43], v[196:199], v[142:145], v[40:43]
	v_mfma_f32_16x16x32_bf16 v[36:39], v[204:207], v[134:137], v[36:39]
	v_mfma_f32_16x16x32_bf16 v[32:35], v[204:207], v[142:145], v[32:35]
	v_mfma_f32_16x16x32_bf16 v[60:63], v[154:157], v[138:141], v[60:63]
	v_mfma_f32_16x16x32_bf16 v[56:59], v[154:157], v[146:149], v[56:59]
	v_mfma_f32_16x16x32_bf16 v[52:55], v[192:195], v[138:141], v[52:55]
	v_mfma_f32_16x16x32_bf16 v[48:51], v[192:195], v[146:149], v[48:51]
	v_mfma_f32_16x16x32_bf16 v[44:47], v[200:203], v[138:141], v[44:47]
	v_mfma_f32_16x16x32_bf16 v[40:43], v[200:203], v[146:149], v[40:43]
	v_mfma_f32_16x16x32_bf16 v[36:39], v[208:211], v[138:141], v[36:39]
	v_mfma_f32_16x16x32_bf16 v[32:35], v[208:211], v[146:149], v[32:35]
	s_setprio 0
	s_setprio 1
	v_mfma_f32_16x16x32_bf16 v[28:31], v[150:153], v[212:215], v[28:31]
	v_mfma_f32_16x16x32_bf16 v[24:27], v[150:153], v[220:223], v[24:27]
	v_mfma_f32_16x16x32_bf16 v[20:23], v[188:191], v[212:215], v[20:23]
	v_mfma_f32_16x16x32_bf16 v[16:19], v[188:191], v[220:223], v[16:19]
	v_mfma_f32_16x16x32_bf16 v[12:15], v[196:199], v[212:215], v[12:15]
	v_mfma_f32_16x16x32_bf16 v[8:11], v[196:199], v[220:223], v[8:11]
	v_mfma_f32_16x16x32_bf16 v[4:7], v[204:207], v[212:215], v[4:7]
	v_mfma_f32_16x16x32_bf16 v[0:3], v[204:207], v[220:223], v[0:3]
	v_mfma_f32_16x16x32_bf16 v[28:31], v[154:157], v[216:219], v[28:31]
	v_mfma_f32_16x16x32_bf16 v[24:27], v[154:157], v[224:227], v[24:27]
	v_mfma_f32_16x16x32_bf16 v[20:23], v[192:195], v[216:219], v[20:23]
	v_mfma_f32_16x16x32_bf16 v[16:19], v[192:195], v[224:227], v[16:19]
	v_mfma_f32_16x16x32_bf16 v[12:15], v[200:203], v[216:219], v[12:15]
	v_mfma_f32_16x16x32_bf16 v[8:11], v[200:203], v[224:227], v[8:11]
	v_mfma_f32_16x16x32_bf16 v[4:7], v[208:211], v[216:219], v[4:7]
	v_mfma_f32_16x16x32_bf16 v[0:3], v[208:211], v[224:227], v[0:3]
	s_setprio 0
	s_barrier
	ds_read_b128 v[188:191], v131
	ds_read_b128 v[192:195], v131 offset:1024
	ds_read_b128 v[196:199], v131 offset:2048
	ds_read_b128 v[200:203], v131 offset:3072
	ds_read_b128 v[136:139], v171 offset:32768
	ds_read_b128 v[204:207], v171 offset:33792
	ds_read_b128 v[208:211], v170 offset:32768
	ds_read_b128 v[212:215], v170 offset:33792
	ds_read_b128 v[216:219], v169 offset:32768
	ds_read_b128 v[220:223], v169 offset:33792
	ds_read_b128 v[224:227], v167 offset:32768
	ds_read_b128 v[228:231], v167 offset:33792
	s_waitcnt vmcnt(2)
	s_barrier
	s_waitcnt lgkmcnt(0)
	s_setprio 1
	s_waitcnt lgkmcnt(0)
	v_mfma_f32_16x16x32_bf16 v[124:127], v[136:139], v[188:191], v[124:127]
	v_mfma_f32_16x16x32_bf16 v[120:123], v[136:139], v[196:199], v[120:123]
	v_mfma_f32_16x16x32_bf16 v[116:119], v[208:211], v[188:191], v[116:119]
	v_mfma_f32_16x16x32_bf16 v[112:115], v[208:211], v[196:199], v[112:115]
	v_mfma_f32_16x16x32_bf16 v[108:111], v[216:219], v[188:191], v[108:111]
	v_mfma_f32_16x16x32_bf16 v[104:107], v[216:219], v[196:199], v[104:107]
	v_mfma_f32_16x16x32_bf16 v[100:103], v[224:227], v[188:191], v[100:103]
	v_mfma_f32_16x16x32_bf16 v[96:99], v[224:227], v[196:199], v[96:99]
	v_mfma_f32_16x16x32_bf16 v[152:155], v[204:207], v[192:195], v[124:127]
	v_mfma_f32_16x16x32_bf16 v[156:159], v[204:207], v[200:203], v[120:123]
	v_mfma_f32_16x16x32_bf16 v[144:147], v[212:215], v[192:195], v[116:119]
	v_mfma_f32_16x16x32_bf16 v[148:151], v[212:215], v[200:203], v[112:115]
	v_mfma_f32_16x16x32_bf16 v[132:135], v[220:223], v[192:195], v[108:111]
	v_mfma_f32_16x16x32_bf16 v[140:143], v[220:223], v[200:203], v[104:107]
	v_mfma_f32_16x16x32_bf16 v[116:119], v[228:231], v[192:195], v[100:103]
	v_mfma_f32_16x16x32_bf16 v[124:127], v[228:231], v[200:203], v[96:99]
	s_setprio 0
	s_barrier
; #define LDA(dst, b, h) for (int m = 0; m < 4; ++m) for (int k = 0; k < 2; ++k) \
;     dst[m][k] = *reinterpret_cast<const bf16x8*>((char*)SA(b, h) + lds_byte(wr * 64 + m * 16 + fr, k * 32 + fq * 8))
; #define LDB(dst, b, h) for (int n = 0; n < 2; ++n) for (int k = 0; k < 2; ++k) \
;     dst[n][k] = *reinterpret_cast<const bf16x8*>((char*)SB(b, h) + lds_byte(wc * 32 + n * 16 + fr, k * 32 + fq * 8))
; #define MMA(ai, bj, At, Bt_) do { __builtin_amdgcn_s_setprio(1); \
;     for (int m = 0; m < 4; ++m) for (int n = 0; n < 2; ++n) for (int k = 0; k < 2; ++k) \
;       acc[ai][bj][m][n] = __builtin_amdgcn_mfma_f32_16x16x32_bf16(At[m][k], Bt_[n][k], acc[ai][bj][m][n], 0, 0, 0); \
;     __builtin_amdgcn_s_setprio(0); } while (0)
; #define WAIT_V(n) asm volatile("s_waitcnt vmcnt(" #n ")" ::: "memory")
; #define WAIT_L(n) asm volatile("s_waitcnt lgkmcnt(" #n ")" ::: "memory")
; #define BAR __builtin_amdgcn_s_barrier()
; __device__ __forceinline__ void gemm_tile(const bf16_t* __restrict__ A, const bf16_t* __restrict__ Bt, int K, int brow, int bcol,
;                                           int mode, const Params& p, char* wsb, const float* xg, float* outg, int S, char* shmc) {
;     ...
;   { LDB(B0, 1, 0); LDA(At, 1, 0); WAIT_V(2); BAR; WAIT_L(0); MMA(0, 0, At, B0); BAR;
;     LDB(B1, 1, 1); WAIT_V(0); BAR; WAIT_L(0); MMA(0, 1, At, B1); BAR;
;     LDA(At, 1, 1); BAR; WAIT_L(0); MMA(1, 0, At, B0); MMA(1, 1, At, B1); BAR; }
;   if (wr == 0) BAR;
	ds_read_b128 v[232:235], v130
	ds_read_b128 v[236:239], v130 offset:1024
	ds_read_b128 v[240:243], v130 offset:2048
	ds_read_b128 v[244:247], v130 offset:3072
	s_waitcnt vmcnt(0)
	s_barrier
	s_waitcnt lgkmcnt(0)
	s_setprio 1
	s_waitcnt lgkmcnt(0)
	v_mfma_f32_16x16x32_bf16 v[92:95], v[136:139], v[232:235], v[92:95]
	v_mfma_f32_16x16x32_bf16 v[88:91], v[136:139], v[240:243], v[88:91]
	v_mfma_f32_16x16x32_bf16 v[84:87], v[208:211], v[232:235], v[84:87]
	v_mfma_f32_16x16x32_bf16 v[80:83], v[208:211], v[240:243], v[80:83]
	v_mfma_f32_16x16x32_bf16 v[76:79], v[216:219], v[232:235], v[76:79]
	v_mfma_f32_16x16x32_bf16 v[72:75], v[216:219], v[240:243], v[72:75]
	v_mfma_f32_16x16x32_bf16 v[68:71], v[224:227], v[232:235], v[68:71]
	v_mfma_f32_16x16x32_bf16 v[64:67], v[224:227], v[240:243], v[64:67]
	v_mfma_f32_16x16x32_bf16 v[128:131], v[204:207], v[236:239], v[92:95]
	v_mfma_f32_16x16x32_bf16 v[136:139], v[204:207], v[244:247], v[88:91]
	v_mfma_f32_16x16x32_bf16 v[112:115], v[212:215], v[236:239], v[84:87]
	v_mfma_f32_16x16x32_bf16 v[120:123], v[212:215], v[244:247], v[80:83]
	v_mfma_f32_16x16x32_bf16 v[104:107], v[220:223], v[236:239], v[76:79]
	v_mfma_f32_16x16x32_bf16 v[108:111], v[220:223], v[244:247], v[72:75]
	v_mfma_f32_16x16x32_bf16 v[96:99], v[228:231], v[236:239], v[68:71]
	v_mfma_f32_16x16x32_bf16 v[100:103], v[228:231], v[244:247], v[64:67]
	s_setprio 0
	s_barrier
	ds_read_b128 v[204:207], v171 offset:49152
	ds_read_b128 v[208:211], v171 offset:50176
	ds_read_b128 v[212:215], v170 offset:49152
	ds_read_b128 v[170:173], v170 offset:50176
	ds_read_b128 v[216:219], v169 offset:49152
	ds_read_b128 v[220:223], v169 offset:50176
	ds_read_b128 v[224:227], v167 offset:49152
	ds_read_b128 v[228:231], v167 offset:50176
	s_barrier
	s_waitcnt lgkmcnt(0)
	s_setprio 1
	s_waitcnt lgkmcnt(0)
	v_mfma_f32_16x16x32_bf16 v[60:63], v[204:207], v[188:191], v[60:63]
	v_mfma_f32_16x16x32_bf16 v[56:59], v[204:207], v[196:199], v[56:59]
	v_mfma_f32_16x16x32_bf16 v[52:55], v[212:215], v[188:191], v[52:55]
	v_mfma_f32_16x16x32_bf16 v[48:51], v[212:215], v[196:199], v[48:51]
	v_mfma_f32_16x16x32_bf16 v[44:47], v[216:219], v[188:191], v[44:47]
	v_mfma_f32_16x16x32_bf16 v[40:43], v[216:219], v[196:199], v[40:43]
	v_mfma_f32_16x16x32_bf16 v[36:39], v[224:227], v[188:191], v[36:39]
	v_mfma_f32_16x16x32_bf16 v[32:35], v[224:227], v[196:199], v[32:35]
	v_mfma_f32_16x16x32_bf16 v[88:91], v[208:211], v[192:195], v[60:63]
	v_mfma_f32_16x16x32_bf16 v[92:95], v[208:211], v[200:203], v[56:59]
	v_mfma_f32_16x16x32_bf16 v[80:83], v[170:173], v[192:195], v[52:55]
	v_mfma_f32_16x16x32_bf16 v[84:87], v[170:173], v[200:203], v[48:51]
	v_mfma_f32_16x16x32_bf16 v[72:75], v[220:223], v[192:195], v[44:47]
	v_mfma_f32_16x16x32_bf16 v[76:79], v[220:223], v[200:203], v[40:43]
	v_mfma_f32_16x16x32_bf16 v[64:67], v[228:231], v[192:195], v[36:39]
	v_mfma_f32_16x16x32_bf16 v[68:71], v[228:231], v[200:203], v[32:35]
	s_setprio 0
	s_setprio 1
	v_mfma_f32_16x16x32_bf16 v[28:31], v[204:207], v[232:235], v[28:31]
	v_mfma_f32_16x16x32_bf16 v[24:27], v[204:207], v[240:243], v[24:27]
	v_mfma_f32_16x16x32_bf16 v[20:23], v[212:215], v[232:235], v[20:23]
	v_mfma_f32_16x16x32_bf16 v[16:19], v[212:215], v[240:243], v[16:19]
	v_mfma_f32_16x16x32_bf16 v[12:15], v[216:219], v[232:235], v[12:15]
	v_mfma_f32_16x16x32_bf16 v[8:11], v[216:219], v[240:243], v[8:11]
	v_mfma_f32_16x16x32_bf16 v[4:7], v[224:227], v[232:235], v[4:7]
	v_mfma_f32_16x16x32_bf16 v[0:3], v[224:227], v[240:243], v[0:3]
	v_mfma_f32_16x16x32_bf16 v[56:59], v[208:211], v[236:239], v[28:31]
	v_mfma_f32_16x16x32_bf16 v[60:63], v[208:211], v[244:247], v[24:27]
	v_mfma_f32_16x16x32_bf16 v[48:51], v[170:173], v[236:239], v[20:23]
	v_mfma_f32_16x16x32_bf16 v[52:55], v[170:173], v[244:247], v[16:19]
	v_mfma_f32_16x16x32_bf16 v[40:43], v[220:223], v[236:239], v[12:15]
	v_mfma_f32_16x16x32_bf16 v[44:47], v[220:223], v[244:247], v[8:11]
	v_mfma_f32_16x16x32_bf16 v[32:35], v[228:231], v[236:239], v[4:7]
	v_mfma_f32_16x16x32_bf16 v[36:39], v[228:231], v[244:247], v[0:3]
	s_setprio 0
	s_movk_i32 s4, 0x100
	v_cmp_gt_u32_e32 vcc, s4, v162
	s_barrier
	s_and_saveexec_b64 s[4:5], vcc
	s_cbranch_execz .LBB0_172
	s_barrier
